# attention LDS-DMA staging with the eight full-wave V-tile DMA issues interleaved between the QK MFMAs
# baseline (speedup 1.0000x reference)
; #define LAS __attribute__((address_space(3)))
; __device__ __forceinline__ void attn_phase(Frame& F, h16* Obr) {
;     ...
;     for (int I = i_lo; I < i_hi; I += i_st) {
;         const AttItem cu = nx;
;         __syncthreads();
;         {   const int ch = tid & 15, r4 = tid >> 4;
; #pragma unroll
;             for (int j = 0; j < 17; ++j) { const bool isv = j >= 8; const int rr = isv ? r4 + 32 * (j - 8) : r4 + 32 * j;
;                 if (j < 16 || tid < 256) *(LAS u32x4*)(lds + (isv ? ATT_V : ATT_K) + att_off(rr, ch)) = kv[j]; } }
.LBB0_723:
	s_waitcnt vmcnt(63) expcnt(7) lgkmcnt(15)
	s_barrier
	s_and_saveexec_b64 s[26:27], s[36:37]
	s_cbranch_execz .Lattn_v17
	s_add_u32 m0, s101, 0x10000
	s_nop 0
	global_load_lds_dwordx4 v[16:17], off

; #define LAS __attribute__((address_space(3)))
; __device__ __forceinline__ void attn_phase(Frame& F, h16* Obr) {
;     ...
;         if (I + i_st < i_hi) { nx = att_decode(I + i_st); ATT_ISSUE(nx); }
;         const int idx0 = cu.idx0, L = cu.L;
;         const int qtok = cu.p + cu.r * (idx0 + 16 * w + q16);
;         f32x4 sc[9];
;         h16x8 kfb[2][4];
; #pragma unroll
;         for (int s = 0; s < 4; ++s) kfb[0][s] = *(const LAS h16x8*)(lds + ATT_K + att_off(16 * w + q16, 4 * s + g));
; #pragma unroll
;         for (int tt = 0; tt < 9; ++tt) {
;             if (tt + 1 < 9) {
; #pragma unroll
;                 for (int s = 0; s < 4; ++s) kfb[(tt + 1) & 1][s] = *(const LAS h16x8*)(lds + ATT_K + att_off(16 * (w + tt + 1) + q16, 4 * s + g)); }
;             asm volatile("" ::: "memory");
;             f32x4 a = {0.f, 0.f, 0.f, 0.f};
; #pragma unroll
;             for (int s = 0; s < 4; ++s) a = __builtin_amdgcn_mfma_f32_16x16x32_f16(kfb[tt & 1][s], Qf[s], a, 0, 0, 0);
;             sc[tt] = a; }
.LBB0_737:
	v_add_u32_e32 v100, s51, v158
	v_mul_lo_u32 v128, s0, v100
	v_add_u32_e32 v100, v160, v164
	ds_read_b128 v[100:103], v100
	v_add_u32_e32 v104, v160, v165
	ds_read_b128 v[104:107], v104
	v_add_u32_e32 v108, v160, v166
	ds_read_b128 v[108:111], v108
	v_add_u32_e32 v129, v168, v164
	ds_read_b128 v[116:119], v129 offset:4096
	v_add_u32_e32 v112, v160, v167
	s_waitcnt vmcnt(20) lgkmcnt(3)
	v_mfma_f32_16x16x32_f16 v[100:103], v[100:103], v[96:99], 0
	ds_read_b128 v[112:115], v112
	v_add_u32_e32 v146, v168, v165
	ds_read_b128 v[120:123], v146 offset:4096
	s_waitcnt lgkmcnt(4)
	v_mfma_f32_16x16x32_f16 v[100:103], v[104:107], v[92:95], v[100:103]
	s_add_u32 m0, s101, 0x0
	s_nop 0
	global_load_lds_dwordx4 v[36:37], off
	v_add_u32_e32 v147, v168, v166
	ds_read_b128 v[124:127], v147 offset:4096
	v_add_u32_e32 v206, v168, v167
	s_waitcnt lgkmcnt(4)
	v_mfma_f32_16x16x32_f16 v[100:103], v[108:111], v[88:91], v[100:103]
	ds_read_b128 v[130:133], v206 offset:4096
	s_waitcnt lgkmcnt(4)
	v_mfma_f32_16x16x32_f16 v[104:107], v[116:119], v[96:99], 0
	s_waitcnt lgkmcnt(3)
	v_mfma_f32_16x16x32_f16 v[100:103], v[112:115], v[84:87], v[100:103]
	ds_read_b128 v[108:111], v129 offset:8192
	ds_read_b128 v[112:115], v146 offset:8192
	ds_read_b128 v[134:137], v147 offset:8192
	ds_read_b128 v[138:141], v206 offset:8192
	s_waitcnt lgkmcnt(6)
	v_mfma_f32_16x16x32_f16 v[104:107], v[120:123], v[92:95], v[104:107]
	s_add_u32 m0, s101, 0x2000
	s_nop 0
	global_load_lds_dwordx4 v[40:41], off
	s_waitcnt lgkmcnt(3)
	v_mfma_f32_16x16x32_f16 v[108:111], v[108:111], v[96:99], 0
	v_mfma_f32_16x16x32_f16 v[104:107], v[124:127], v[88:91], v[104:107]
	s_waitcnt lgkmcnt(2)
	v_mfma_f32_16x16x32_f16 v[108:111], v[112:115], v[92:95], v[108:111]
	v_mfma_f32_16x16x32_f16 v[104:107], v[130:133], v[84:87], v[104:107]
	s_add_u32 m0, s101, 0x4000
	s_nop 0
	global_load_lds_dwordx4 v[44:45], off
	ds_read_b128 v[116:119], v129 offset:12288
	ds_read_b128 v[120:123], v146 offset:12288
	ds_read_b128 v[124:127], v147 offset:12288
	ds_read_b128 v[130:133], v206 offset:12288
	s_waitcnt lgkmcnt(5)
	v_mfma_f32_16x16x32_f16 v[108:111], v[134:137], v[88:91], v[108:111]
	s_waitcnt lgkmcnt(3)
	v_mfma_f32_16x16x32_f16 v[112:115], v[116:119], v[96:99], 0
	v_mfma_f32_16x16x32_f16 v[108:111], v[138:141], v[84:87], v[108:111]
	ds_read_b128 v[134:137], v129 offset:16384
	ds_read_b128 v[138:141], v146 offset:16384
	ds_read_b128 v[142:145], v147 offset:16384
	ds_read_b128 v[152:155], v206 offset:16384
	s_waitcnt lgkmcnt(6)
	v_mfma_f32_16x16x32_f16 v[112:115], v[120:123], v[92:95], v[112:115]
	s_add_u32 m0, s101, 0x6000
	s_nop 0
	global_load_lds_dwordx4 v[48:49], off
	s_waitcnt lgkmcnt(3)
	v_mfma_f32_16x16x32_f16 v[116:119], v[134:137], v[96:99], 0
	v_mfma_f32_16x16x32_f16 v[112:115], v[124:127], v[88:91], v[112:115]
	s_waitcnt lgkmcnt(2)
	v_mfma_f32_16x16x32_f16 v[116:119], v[138:141], v[92:95], v[116:119]
	v_mfma_f32_16x16x32_f16 v[112:115], v[130:133], v[84:87], v[112:115]
	s_add_u32 m0, s101, 0x8000
	s_nop 0
	global_load_lds_dwordx4 v[52:53], off
	ds_read_b128 v[120:123], v129 offset:20480
	ds_read_b128 v[124:127], v146 offset:20480
	ds_read_b128 v[130:133], v147 offset:20480
	ds_read_b128 v[194:197], v206 offset:20480
	s_waitcnt lgkmcnt(5)
	v_mfma_f32_16x16x32_f16 v[116:119], v[142:145], v[88:91], v[116:119]
	s_waitcnt lgkmcnt(3)
	v_mfma_f32_16x16x32_f16 v[120:123], v[120:123], v[96:99], 0
	v_mfma_f32_16x16x32_f16 v[116:119], v[152:155], v[84:87], v[116:119]
	ds_read_b128 v[134:137], v129 offset:24576
	ds_read_b128 v[138:141], v146 offset:24576
	ds_read_b128 v[142:145], v147 offset:24576
	ds_read_b128 v[152:155], v206 offset:24576
	s_waitcnt lgkmcnt(6)
	v_mfma_f32_16x16x32_f16 v[120:123], v[124:127], v[92:95], v[120:123]
	s_add_u32 m0, s101, 0xa000
	s_nop 0
	global_load_lds_dwordx4 v[56:57], off
	s_waitcnt lgkmcnt(3)
	v_mfma_f32_16x16x32_f16 v[124:127], v[134:137], v[96:99], 0
	s_waitcnt lgkmcnt(2)
	v_mfma_f32_16x16x32_f16 v[124:127], v[138:141], v[92:95], v[124:127]
	v_mfma_f32_16x16x32_f16 v[120:123], v[130:133], v[88:91], v[120:123]
	s_waitcnt lgkmcnt(1)
	v_mfma_f32_16x16x32_f16 v[124:127], v[142:145], v[88:91], v[124:127]
	s_add_u32 m0, s101, 0xc000
	s_nop 0
	global_load_lds_dwordx4 v[60:61], off
	v_mfma_f32_16x16x32_f16 v[120:123], v[194:197], v[84:87], v[120:123]
	ds_read_b128 v[130:133], v129 offset:28672
	ds_read_b128 v[194:197], v146 offset:28672
	ds_read_b128 v[198:201], v147 offset:28672
	ds_read_b128 v[202:205], v206 offset:28672
	s_waitcnt lgkmcnt(4)
	v_mfma_f32_16x16x32_f16 v[124:127], v[152:155], v[84:87], v[124:127]
	ds_read_b128 v[134:137], v129 offset:32768
	ds_read_b128 v[138:141], v146 offset:32768
	ds_read_b128 v[142:145], v147 offset:32768
	ds_read_b128 v[152:155], v206 offset:32768
	s_waitcnt lgkmcnt(7)
	v_mfma_f32_16x16x32_f16 v[130:133], v[130:133], v[96:99], 0
	s_waitcnt lgkmcnt(3)
	v_mfma_f32_16x16x32_f16 v[96:99], v[134:137], v[96:99], 0
	s_add_u32 m0, s101, 0xe000
	s_nop 0
	global_load_lds_dwordx4 v[64:65], off
	v_mfma_f32_16x16x32_f16 v[130:133], v[194:197], v[92:95], v[130:133]
	s_waitcnt lgkmcnt(2)
	v_mfma_f32_16x16x32_f16 v[92:95], v[138:141], v[92:95], v[96:99]
	v_mfma_f32_16x16x32_f16 v[130:133], v[198:201], v[88:91], v[130:133]
	s_waitcnt lgkmcnt(1)
	v_mfma_f32_16x16x32_f16 v[88:91], v[142:145], v[88:91], v[92:95]
	v_mfma_f32_16x16x32_f16 v[130:133], v[202:205], v[84:87], v[130:133]
	s_waitcnt lgkmcnt(0)
	v_mfma_f32_16x16x32_f16 v[84:87], v[152:155], v[84:87], v[88:91]
	s_cmp_ge_i32 s17, s16
	s_waitcnt vmcnt(0) lgkmcnt(0)
	s_barrier
	s_cbranch_scc1 .LBB0_731
	s_mul_hi_i32 s1, s17, 0x2aaaaaab
	s_lshr_b32 s2, s1, 31
	s_ashr_i32 s1, s1, 3
	s_add_i32 s1, s1, s2
	s_mul_i32 s2, s1, 0xffffffd0
	s_add_i32 s2, s17, s2
	s_cmp_lt_i32 s2, 16
	s_cbranch_scc1 .LBB0_732
	s_cmp_gt_u32 s2, 31
	s_mov_b64 s[26:27], -1
	s_cbranch_scc0 .LBB0_729
	s_sub_i32 s19, s2, 32
	s_mov_b64 s[26:27], 0
